# row-sum cross-lane reduction steps in the P2/P7/P9 epilogues: ds_bpermute round trips replaced by v_permlane16/32_swap (same sums)
# speedup vs baseline: 1.0035x; 1.0022x over previous
.LBB0_426:
	v_lshl_add_u32 v144, s89, 8, v182
	v_ashrrev_i32_e32 v145, 31, v144
	v_lshl_or_b32 v146, s90, 8, v184
	v_pk_mul_f32 v[148:149], v[112:113], 0.5 op_sel_hi:[1,0]
	v_lshlrev_b64 v[112:113], 11, v[144:145]
	v_ashrrev_i32_e32 v147, 31, v146
	v_lshl_add_u64 v[112:113], s[22:23], 0, v[112:113]
	v_cndmask_b32_e64 v154, 0, 1, s[68:69]
	v_pk_mul_f32 v[114:115], v[114:115], 0.5 op_sel_hi:[1,0]
	v_pk_mul_f32 v[118:119], v[118:119], 0.5 op_sel_hi:[1,0]
	v_pk_mul_f32 v[116:117], v[116:117], 0.5 op_sel_hi:[1,0]
	v_cvt_pk_bf16_f32 v150, v148, v149
	v_cvt_pk_bf16_f32 v151, v114, v115
	v_lshl_add_u64 v[112:113], v[146:147], 1, v[112:113]
	v_cvt_pk_bf16_f32 v152, v116, v117
	v_cvt_pk_bf16_f32 v153, v118, v119
	v_pk_mul_f32 v[122:123], v[122:123], 0.5 op_sel_hi:[1,0]
	v_pk_mul_f32 v[120:121], v[120:121], 0.5 op_sel_hi:[1,0]
	v_pk_mul_f32 v[126:127], v[126:127], 0.5 op_sel_hi:[1,0]
	v_pk_mul_f32 v[124:125], v[124:125], 0.5 op_sel_hi:[1,0]
	v_cmp_ne_u32_e64 s[8:9], 1, v154
	s_andn2_b64 vcc, exec, s[68:69]
	global_store_dwordx4 v[112:113], v[150:153], off
	s_nop 1
	v_cvt_pk_bf16_f32 v150, v120, v121
	v_cvt_pk_bf16_f32 v151, v122, v123
	v_cvt_pk_bf16_f32 v152, v124, v125
	v_cvt_pk_bf16_f32 v153, v126, v127
	global_store_dwordx4 v[112:113], v[150:153], off offset:256
	s_cbranch_vccnz .LBB0_430
	v_mul_f32_e32 v117, v117, v117
	v_fmac_f32_e32 v117, v116, v116
	v_mul_f32_e32 v116, v149, v149
	v_mul_f32_e32 v115, v115, v115
	v_fmac_f32_e32 v116, v148, v148
	v_fmac_f32_e32 v115, v114, v114
	v_mul_f32_e32 v119, v119, v119
	v_add_f32_e32 v114, v116, v115
	v_fmac_f32_e32 v119, v118, v118
	v_add_f32_e32 v114, v114, v117
	v_mul_f32_e32 v117, v121, v121
	v_mul_f32_e32 v118, v123, v123
	v_mul_f32_e32 v116, v125, v125
	v_fmac_f32_e32 v117, v120, v120
	v_fmac_f32_e32 v118, v122, v122
	v_mul_f32_e32 v115, v127, v127
	v_fmac_f32_e32 v116, v124, v124
	v_add_f32_e32 v117, v117, v118
	v_fmac_f32_e32 v115, v126, v126
	v_add_f32_e32 v116, v117, v116
	v_add_f32_e32 v114, v119, v114
	v_add_f32_e32 v115, v115, v116
	v_and_b32_e32 v116, 64, v186
	v_add_f32_e32 v114, v114, v115
	v_xor_b32_e32 v115, 16, v186
	v_add_u32_e32 v116, 64, v116
	v_cmp_lt_i32_e32 vcc, v115, v116
	s_nop 1
	v_cndmask_b32_e32 v115, v186, v115, vcc
	v_lshlrev_b32_e32 v115, 2, v115
	v_mov_b32_e32 v115, v114
	s_nop 1
	v_permlane16_swap_b32_e32 v114, v115
	s_nop 1
	s_waitcnt lgkmcnt(0)
	v_add_f32_e32 v114, v114, v115
	v_xor_b32_e32 v115, 32, v186
	v_cmp_lt_i32_e32 vcc, v115, v116
	s_nop 1
	v_cndmask_b32_e32 v115, v186, v115, vcc
	v_lshlrev_b32_e32 v115, 2, v115
	v_mov_b32_e32 v115, v114
	s_nop 1
	v_permlane32_swap_b32_e32 v114, v115
	s_nop 1
	s_and_saveexec_b64 s[64:65], s[4:5]
	s_cbranch_execz .LBB0_429
	v_lshl_add_u64 v[116:117], v[144:145], 2, s[28:29]
	s_waitcnt lgkmcnt(0)
	v_add_f32_e32 v114, v114, v115
	global_atomic_add_f32 v[116:117], v114, off

.LBB0_430:
	v_or_b32_e32 v118, 16, v144
	v_ashrrev_i32_e32 v119, 31, v118
	v_lshlrev_b64 v[118:119], 11, v[118:119]
	v_lshl_add_u64 v[118:119], s[22:23], 0, v[118:119]
	v_pk_mul_f32 v[98:99], v[98:99], 0.5 op_sel_hi:[1,0]
	v_pk_mul_f32 v[96:97], v[96:97], 0.5 op_sel_hi:[1,0]
	v_pk_mul_f32 v[102:103], v[102:103], 0.5 op_sel_hi:[1,0]
	v_pk_mul_f32 v[100:101], v[100:101], 0.5 op_sel_hi:[1,0]
	v_cvt_pk_bf16_f32 v114, v96, v97
	s_waitcnt lgkmcnt(0)
	v_cvt_pk_bf16_f32 v115, v98, v99
	v_lshl_add_u64 v[118:119], v[146:147], 1, v[118:119]
	v_cvt_pk_bf16_f32 v116, v100, v101
	v_cvt_pk_bf16_f32 v117, v102, v103
	v_pk_mul_f32 v[106:107], v[106:107], 0.5 op_sel_hi:[1,0]
	v_pk_mul_f32 v[104:105], v[104:105], 0.5 op_sel_hi:[1,0]
	v_pk_mul_f32 v[110:111], v[110:111], 0.5 op_sel_hi:[1,0]
	v_pk_mul_f32 v[108:109], v[108:109], 0.5 op_sel_hi:[1,0]
	s_and_b64 vcc, exec, s[8:9]
	global_store_dwordx4 v[118:119], v[114:117], off
	s_nop 1
	v_cvt_pk_bf16_f32 v114, v104, v105
	v_cvt_pk_bf16_f32 v115, v106, v107
	v_cvt_pk_bf16_f32 v116, v108, v109
	v_cvt_pk_bf16_f32 v117, v110, v111
	global_store_dwordx4 v[118:119], v[114:117], off offset:256
	s_cbranch_vccnz .LBB0_434
	v_mul_f32_e32 v101, v101, v101
	v_mul_f32_e32 v97, v97, v97
	v_fmac_f32_e32 v101, v100, v100
	v_fmac_f32_e32 v97, v96, v96
	v_mul_f32_e32 v96, v99, v99
	v_mul_f32_e32 v99, v105, v105
	v_mul_f32_e32 v100, v107, v107
	v_fmac_f32_e32 v96, v98, v98
	v_mul_f32_e32 v98, v109, v109
	v_fmac_f32_e32 v99, v104, v104
	v_fmac_f32_e32 v100, v106, v106
	v_mul_f32_e32 v103, v103, v103
	v_add_f32_e32 v96, v97, v96
	v_mul_f32_e32 v97, v111, v111
	v_fmac_f32_e32 v98, v108, v108
	v_add_f32_e32 v99, v99, v100
	v_fmac_f32_e32 v103, v102, v102
	v_add_f32_e32 v96, v96, v101
	v_fmac_f32_e32 v97, v110, v110
	v_add_f32_e32 v98, v99, v98
	v_add_f32_e32 v96, v103, v96
	v_add_f32_e32 v97, v97, v98
	v_and_b32_e32 v98, 64, v186
	v_add_f32_e32 v96, v96, v97
	v_xor_b32_e32 v97, 16, v186
	v_add_u32_e32 v98, 64, v98
	v_cmp_lt_i32_e32 vcc, v97, v98
	s_nop 1
	v_cndmask_b32_e32 v97, v186, v97, vcc
	v_lshlrev_b32_e32 v97, 2, v97
	v_mov_b32_e32 v97, v96
	s_nop 1
	v_permlane16_swap_b32_e32 v96, v97
	s_nop 1
	s_waitcnt lgkmcnt(0)
	v_add_f32_e32 v96, v96, v97
	v_xor_b32_e32 v97, 32, v186
	v_cmp_lt_i32_e32 vcc, v97, v98
	s_nop 1
	v_cndmask_b32_e32 v97, v186, v97, vcc
	v_lshlrev_b32_e32 v97, 2, v97
	v_mov_b32_e32 v97, v96
	s_nop 1
	v_permlane32_swap_b32_e32 v96, v97
	s_nop 1
	s_and_saveexec_b64 s[64:65], s[4:5]
	s_cbranch_execz .LBB0_433
	v_lshl_add_u64 v[98:99], v[144:145], 2, s[28:29]
	s_waitcnt lgkmcnt(0)
	v_add_f32_e32 v96, v96, v97
	global_atomic_add_f32 v[98:99], v96, off offset:64

.LBB0_434:
	v_or_b32_e32 v100, 32, v144
	v_ashrrev_i32_e32 v101, 31, v100
	v_lshlrev_b64 v[100:101], 11, v[100:101]
	v_lshl_add_u64 v[100:101], s[22:23], 0, v[100:101]
	v_pk_mul_f32 v[82:83], v[82:83], 0.5 op_sel_hi:[1,0]
	v_pk_mul_f32 v[80:81], v[80:81], 0.5 op_sel_hi:[1,0]
	v_pk_mul_f32 v[86:87], v[86:87], 0.5 op_sel_hi:[1,0]
	v_pk_mul_f32 v[84:85], v[84:85], 0.5 op_sel_hi:[1,0]
	v_cvt_pk_bf16_f32 v96, v80, v81
	s_waitcnt lgkmcnt(0)
	v_cvt_pk_bf16_f32 v97, v82, v83
	v_lshl_add_u64 v[100:101], v[146:147], 1, v[100:101]
	v_cvt_pk_bf16_f32 v98, v84, v85
	v_cvt_pk_bf16_f32 v99, v86, v87
	v_pk_mul_f32 v[90:91], v[90:91], 0.5 op_sel_hi:[1,0]
	v_pk_mul_f32 v[88:89], v[88:89], 0.5 op_sel_hi:[1,0]
	v_pk_mul_f32 v[94:95], v[94:95], 0.5 op_sel_hi:[1,0]
	v_pk_mul_f32 v[92:93], v[92:93], 0.5 op_sel_hi:[1,0]
	s_and_b64 vcc, exec, s[8:9]
	global_store_dwordx4 v[100:101], v[96:99], off
	s_nop 1
	v_cvt_pk_bf16_f32 v96, v88, v89
	v_cvt_pk_bf16_f32 v97, v90, v91
	v_cvt_pk_bf16_f32 v98, v92, v93
	v_cvt_pk_bf16_f32 v99, v94, v95
	global_store_dwordx4 v[100:101], v[96:99], off offset:256
	s_cbranch_vccnz .LBB0_438
	v_mul_f32_e32 v85, v85, v85
	v_mul_f32_e32 v81, v81, v81
	v_fmac_f32_e32 v85, v84, v84
	v_fmac_f32_e32 v81, v80, v80
	v_mul_f32_e32 v80, v83, v83
	v_mul_f32_e32 v83, v89, v89
	v_mul_f32_e32 v84, v91, v91
	v_fmac_f32_e32 v80, v82, v82
	v_mul_f32_e32 v82, v93, v93
	v_fmac_f32_e32 v83, v88, v88
	v_fmac_f32_e32 v84, v90, v90
	v_mul_f32_e32 v87, v87, v87
	v_add_f32_e32 v80, v81, v80
	v_mul_f32_e32 v81, v95, v95
	v_fmac_f32_e32 v82, v92, v92
	v_add_f32_e32 v83, v83, v84
	v_fmac_f32_e32 v87, v86, v86
	v_add_f32_e32 v80, v80, v85
	v_fmac_f32_e32 v81, v94, v94
	v_add_f32_e32 v82, v83, v82
	v_add_f32_e32 v80, v87, v80
	v_add_f32_e32 v81, v81, v82
	v_and_b32_e32 v82, 64, v186
	v_add_f32_e32 v80, v80, v81
	v_xor_b32_e32 v81, 16, v186
	v_add_u32_e32 v82, 64, v82
	v_cmp_lt_i32_e32 vcc, v81, v82
	s_nop 1
	v_cndmask_b32_e32 v81, v186, v81, vcc
	v_lshlrev_b32_e32 v81, 2, v81
	v_mov_b32_e32 v81, v80
	s_nop 1
	v_permlane16_swap_b32_e32 v80, v81
	s_nop 1
	s_waitcnt lgkmcnt(0)
	v_add_f32_e32 v80, v80, v81
	v_xor_b32_e32 v81, 32, v186
	v_cmp_lt_i32_e32 vcc, v81, v82
	s_nop 1
	v_cndmask_b32_e32 v81, v186, v81, vcc
	v_lshlrev_b32_e32 v81, 2, v81
	v_mov_b32_e32 v81, v80
	s_nop 1
	v_permlane32_swap_b32_e32 v80, v81
	s_nop 1
	s_and_saveexec_b64 s[64:65], s[4:5]
	s_cbranch_execz .LBB0_437
	v_lshl_add_u64 v[82:83], v[144:145], 2, s[28:29]
	s_waitcnt lgkmcnt(0)
	v_add_f32_e32 v80, v80, v81
	global_atomic_add_f32 v[82:83], v80, off offset:128

.LBB0_438:
	v_or_b32_e32 v84, 48, v144
	v_ashrrev_i32_e32 v85, 31, v84
	v_lshlrev_b64 v[84:85], 11, v[84:85]
	v_lshl_add_u64 v[84:85], s[22:23], 0, v[84:85]
	v_pk_mul_f32 v[50:51], v[50:51], 0.5 op_sel_hi:[1,0]
	v_pk_mul_f32 v[48:49], v[48:49], 0.5 op_sel_hi:[1,0]
	v_pk_mul_f32 v[58:59], v[58:59], 0.5 op_sel_hi:[1,0]
	v_pk_mul_f32 v[56:57], v[56:57], 0.5 op_sel_hi:[1,0]
	v_cvt_pk_bf16_f32 v80, v48, v49
	s_waitcnt lgkmcnt(0)
	v_cvt_pk_bf16_f32 v81, v50, v51
	v_lshl_add_u64 v[84:85], v[146:147], 1, v[84:85]
	v_cvt_pk_bf16_f32 v82, v56, v57
	v_cvt_pk_bf16_f32 v83, v58, v59
	v_pk_mul_f32 v[66:67], v[66:67], 0.5 op_sel_hi:[1,0]
	v_pk_mul_f32 v[64:65], v[64:65], 0.5 op_sel_hi:[1,0]
	v_pk_mul_f32 v[74:75], v[74:75], 0.5 op_sel_hi:[1,0]
	v_pk_mul_f32 v[72:73], v[72:73], 0.5 op_sel_hi:[1,0]
	s_and_b64 vcc, exec, s[8:9]
	global_store_dwordx4 v[84:85], v[80:83], off
	s_nop 1
	v_cvt_pk_bf16_f32 v80, v64, v65
	v_cvt_pk_bf16_f32 v81, v66, v67
	v_cvt_pk_bf16_f32 v82, v72, v73
	v_cvt_pk_bf16_f32 v83, v74, v75
	global_store_dwordx4 v[84:85], v[80:83], off offset:256
	s_cbranch_vccnz .LBB0_442
	v_mul_f32_e32 v57, v57, v57
	v_mul_f32_e32 v49, v49, v49
	v_fmac_f32_e32 v57, v56, v56
	v_fmac_f32_e32 v49, v48, v48
	v_mul_f32_e32 v48, v51, v51
	v_mul_f32_e32 v51, v65, v65
	v_mul_f32_e32 v56, v67, v67
	v_fmac_f32_e32 v48, v50, v50
	v_mul_f32_e32 v50, v73, v73
	v_fmac_f32_e32 v51, v64, v64
	v_fmac_f32_e32 v56, v66, v66
	v_mul_f32_e32 v59, v59, v59
	v_add_f32_e32 v48, v49, v48
	v_mul_f32_e32 v49, v75, v75
	v_fmac_f32_e32 v50, v72, v72
	v_add_f32_e32 v51, v51, v56
	v_fmac_f32_e32 v59, v58, v58
	v_add_f32_e32 v48, v48, v57
	v_fmac_f32_e32 v49, v74, v74
	v_add_f32_e32 v50, v51, v50
	v_add_f32_e32 v48, v59, v48
	v_add_f32_e32 v49, v49, v50
	v_and_b32_e32 v50, 64, v186
	v_add_f32_e32 v48, v48, v49
	v_xor_b32_e32 v49, 16, v186
	v_add_u32_e32 v50, 64, v50
	v_cmp_lt_i32_e32 vcc, v49, v50
	s_nop 1
	v_cndmask_b32_e32 v49, v186, v49, vcc
	v_lshlrev_b32_e32 v49, 2, v49
	v_mov_b32_e32 v49, v48
	s_nop 1
	v_permlane16_swap_b32_e32 v48, v49
	s_nop 1
	s_waitcnt lgkmcnt(0)
	v_add_f32_e32 v48, v48, v49
	v_xor_b32_e32 v49, 32, v186
	v_cmp_lt_i32_e32 vcc, v49, v50
	s_nop 1
	v_cndmask_b32_e32 v49, v186, v49, vcc
	v_lshlrev_b32_e32 v49, 2, v49
	v_mov_b32_e32 v49, v48
	s_nop 1
	v_permlane32_swap_b32_e32 v48, v49
	s_nop 1
	s_and_saveexec_b64 s[64:65], s[4:5]
	s_cbranch_execz .LBB0_441
	v_lshl_add_u64 v[50:51], v[144:145], 2, s[28:29]
	s_waitcnt lgkmcnt(0)
	v_add_f32_e32 v48, v48, v49
	global_atomic_add_f32 v[50:51], v48, off offset:192

.LBB0_442:
	v_pk_mul_f32 v[50:51], v[52:53], 0.5 op_sel_hi:[1,0]
	v_pk_mul_f32 v[52:53], v[60:61], 0.5 op_sel_hi:[1,0]
	v_add_co_u32_e32 v60, vcc, s21, v112
	s_waitcnt lgkmcnt(0)
	v_pk_mul_f32 v[48:49], v[54:55], 0.5 op_sel_hi:[1,0]
	v_pk_mul_f32 v[54:55], v[62:63], 0.5 op_sel_hi:[1,0]
	v_cvt_pk_bf16_f32 v56, v50, v51
	v_cvt_pk_bf16_f32 v57, v48, v49
	v_cvt_pk_bf16_f32 v58, v52, v53
	v_addc_co_u32_e32 v61, vcc, 0, v113, vcc
	v_cvt_pk_bf16_f32 v59, v54, v55
	v_lshl_add_u64 v[72:73], v[112:113], 0, s[10:11]
	global_store_dwordx4 v[60:61], v[56:59], off
	v_pk_mul_f32 v[62:63], v[78:79], 0.5 op_sel_hi:[1,0]
	v_pk_mul_f32 v[60:61], v[76:77], 0.5 op_sel_hi:[1,0]
	v_pk_mul_f32 v[56:57], v[70:71], 0.5 op_sel_hi:[1,0]
	v_pk_mul_f32 v[58:59], v[68:69], 0.5 op_sel_hi:[1,0]
	s_and_b64 vcc, exec, s[8:9]
	v_cvt_pk_bf16_f32 v64, v58, v59
	v_cvt_pk_bf16_f32 v65, v56, v57
	v_cvt_pk_bf16_f32 v66, v60, v61
	v_cvt_pk_bf16_f32 v67, v62, v63
	global_store_dwordx4 v[72:73], v[64:67], off offset:256
	s_cbranch_vccnz .LBB0_446
	v_mul_f32_e32 v51, v51, v51
	v_mul_f32_e32 v49, v49, v49
	v_mul_f32_e32 v53, v53, v53
	v_fmac_f32_e32 v51, v50, v50
	v_fmac_f32_e32 v49, v48, v48
	v_fmac_f32_e32 v53, v52, v52
	v_add_f32_e32 v48, v51, v49
	v_mul_f32_e32 v51, v59, v59
	v_mul_f32_e32 v52, v57, v57
	v_mul_f32_e32 v50, v61, v61
	v_fmac_f32_e32 v51, v58, v58
	v_fmac_f32_e32 v52, v56, v56
	v_mul_f32_e32 v55, v55, v55
	v_mul_f32_e32 v49, v63, v63
	v_fmac_f32_e32 v50, v60, v60
	v_add_f32_e32 v51, v51, v52
	v_fmac_f32_e32 v55, v54, v54
	v_add_f32_e32 v48, v48, v53
	v_fmac_f32_e32 v49, v62, v62
	v_add_f32_e32 v50, v51, v50
	v_add_f32_e32 v48, v55, v48
	v_add_f32_e32 v49, v49, v50
	v_and_b32_e32 v50, 64, v186
	v_add_f32_e32 v48, v48, v49
	v_xor_b32_e32 v49, 16, v186
	v_add_u32_e32 v50, 64, v50
	v_cmp_lt_i32_e32 vcc, v49, v50
	s_nop 1
	v_cndmask_b32_e32 v49, v186, v49, vcc
	v_lshlrev_b32_e32 v49, 2, v49
	v_mov_b32_e32 v49, v48
	s_nop 1
	v_permlane16_swap_b32_e32 v48, v49
	s_nop 1
	s_waitcnt lgkmcnt(0)
	v_add_f32_e32 v48, v48, v49
	v_xor_b32_e32 v49, 32, v186
	v_cmp_lt_i32_e32 vcc, v49, v50
	s_nop 1
	v_cndmask_b32_e32 v49, v186, v49, vcc
	v_lshlrev_b32_e32 v49, 2, v49
	v_mov_b32_e32 v49, v48
	s_nop 1
	v_permlane32_swap_b32_e32 v48, v49
	s_nop 1
	s_and_saveexec_b64 s[64:65], s[4:5]
	s_cbranch_execz .LBB0_445
	v_lshl_add_u64 v[50:51], v[144:145], 2, s[28:29]
	s_waitcnt lgkmcnt(0)
	v_add_f32_e32 v48, v48, v49
	global_atomic_add_f32 v[50:51], v48, off offset:512

.LBB0_446:
	v_add_co_u32_e32 v54, vcc, s48, v112
	v_pk_mul_f32 v[34:35], v[34:35], 0.5 op_sel_hi:[1,0]
	s_nop 0
	v_addc_co_u32_e32 v55, vcc, 0, v113, vcc
	v_pk_mul_f32 v[32:33], v[32:33], 0.5 op_sel_hi:[1,0]
	v_pk_mul_f32 v[38:39], v[38:39], 0.5 op_sel_hi:[1,0]
	v_pk_mul_f32 v[36:37], v[36:37], 0.5 op_sel_hi:[1,0]
	v_cvt_pk_bf16_f32 v48, v32, v33
	s_waitcnt lgkmcnt(0)
	v_cvt_pk_bf16_f32 v49, v34, v35
	v_lshl_add_u64 v[52:53], v[112:113], 0, s[12:13]
	v_cvt_pk_bf16_f32 v50, v36, v37
	v_cvt_pk_bf16_f32 v51, v38, v39
	v_pk_mul_f32 v[42:43], v[42:43], 0.5 op_sel_hi:[1,0]
	v_pk_mul_f32 v[40:41], v[40:41], 0.5 op_sel_hi:[1,0]
	v_pk_mul_f32 v[46:47], v[46:47], 0.5 op_sel_hi:[1,0]
	v_pk_mul_f32 v[44:45], v[44:45], 0.5 op_sel_hi:[1,0]
	s_and_b64 vcc, exec, s[8:9]
	global_store_dwordx4 v[54:55], v[48:51], off
	s_nop 1
	v_cvt_pk_bf16_f32 v48, v40, v41
	v_cvt_pk_bf16_f32 v49, v42, v43
	v_cvt_pk_bf16_f32 v50, v44, v45
	v_cvt_pk_bf16_f32 v51, v46, v47
	global_store_dwordx4 v[52:53], v[48:51], off offset:256
	s_cbranch_vccnz .LBB0_450
	v_mul_f32_e32 v37, v37, v37
	v_mul_f32_e32 v33, v33, v33
	v_fmac_f32_e32 v37, v36, v36
	v_fmac_f32_e32 v33, v32, v32
	v_mul_f32_e32 v32, v35, v35
	v_mul_f32_e32 v35, v41, v41
	v_mul_f32_e32 v36, v43, v43
	v_fmac_f32_e32 v32, v34, v34
	v_mul_f32_e32 v34, v45, v45
	v_fmac_f32_e32 v35, v40, v40
	v_fmac_f32_e32 v36, v42, v42
	v_mul_f32_e32 v39, v39, v39
	v_add_f32_e32 v32, v33, v32
	v_mul_f32_e32 v33, v47, v47
	v_fmac_f32_e32 v34, v44, v44
	v_add_f32_e32 v35, v35, v36
	v_fmac_f32_e32 v39, v38, v38
	v_add_f32_e32 v32, v32, v37
	v_fmac_f32_e32 v33, v46, v46
	v_add_f32_e32 v34, v35, v34
	v_add_f32_e32 v32, v39, v32
	v_add_f32_e32 v33, v33, v34
	v_and_b32_e32 v34, 64, v186
	v_add_f32_e32 v32, v32, v33
	v_xor_b32_e32 v33, 16, v186
	v_add_u32_e32 v34, 64, v34
	v_cmp_lt_i32_e32 vcc, v33, v34
	s_nop 1
	v_cndmask_b32_e32 v33, v186, v33, vcc
	v_lshlrev_b32_e32 v33, 2, v33
	v_mov_b32_e32 v33, v32
	s_nop 1
	v_permlane16_swap_b32_e32 v32, v33
	s_nop 1
	s_waitcnt lgkmcnt(0)
	v_add_f32_e32 v32, v32, v33
	v_xor_b32_e32 v33, 32, v186
	v_cmp_lt_i32_e32 vcc, v33, v34
	s_nop 1
	v_cndmask_b32_e32 v33, v186, v33, vcc
	v_lshlrev_b32_e32 v33, 2, v33
	v_mov_b32_e32 v33, v32
	s_nop 1
	v_permlane32_swap_b32_e32 v32, v33
	s_nop 1
	s_and_saveexec_b64 s[64:65], s[4:5]
	s_cbranch_execz .LBB0_449
	v_lshl_add_u64 v[34:35], v[144:145], 2, s[28:29]
	s_waitcnt lgkmcnt(0)
	v_add_f32_e32 v32, v32, v33
	global_atomic_add_f32 v[34:35], v32, off offset:576

.LBB0_450:
	v_add_co_u32_e32 v38, vcc, s49, v112
	v_pk_mul_f32 v[18:19], v[18:19], 0.5 op_sel_hi:[1,0]
	s_nop 0
	v_addc_co_u32_e32 v39, vcc, 0, v113, vcc
	v_pk_mul_f32 v[16:17], v[16:17], 0.5 op_sel_hi:[1,0]
	v_pk_mul_f32 v[22:23], v[22:23], 0.5 op_sel_hi:[1,0]
	v_pk_mul_f32 v[20:21], v[20:21], 0.5 op_sel_hi:[1,0]
	v_cvt_pk_bf16_f32 v32, v16, v17
	s_waitcnt lgkmcnt(0)
	v_cvt_pk_bf16_f32 v33, v18, v19
	v_lshl_add_u64 v[36:37], v[112:113], 0, s[14:15]
	v_cvt_pk_bf16_f32 v34, v20, v21
	v_cvt_pk_bf16_f32 v35, v22, v23
	v_pk_mul_f32 v[26:27], v[26:27], 0.5 op_sel_hi:[1,0]
	v_pk_mul_f32 v[24:25], v[24:25], 0.5 op_sel_hi:[1,0]
	v_pk_mul_f32 v[30:31], v[30:31], 0.5 op_sel_hi:[1,0]
	v_pk_mul_f32 v[28:29], v[28:29], 0.5 op_sel_hi:[1,0]
	s_and_b64 vcc, exec, s[8:9]
	global_store_dwordx4 v[38:39], v[32:35], off
	s_nop 1
	v_cvt_pk_bf16_f32 v32, v24, v25
	v_cvt_pk_bf16_f32 v33, v26, v27
	v_cvt_pk_bf16_f32 v34, v28, v29
	v_cvt_pk_bf16_f32 v35, v30, v31
	global_store_dwordx4 v[36:37], v[32:35], off offset:256
	s_cbranch_vccnz .LBB0_454
	v_mul_f32_e32 v21, v21, v21
	v_mul_f32_e32 v17, v17, v17
	v_fmac_f32_e32 v21, v20, v20
	v_fmac_f32_e32 v17, v16, v16
	v_mul_f32_e32 v16, v19, v19
	v_mul_f32_e32 v19, v25, v25
	v_mul_f32_e32 v20, v27, v27
	v_fmac_f32_e32 v16, v18, v18
	v_mul_f32_e32 v18, v29, v29
	v_fmac_f32_e32 v19, v24, v24
	v_fmac_f32_e32 v20, v26, v26
	v_mul_f32_e32 v23, v23, v23
	v_add_f32_e32 v16, v17, v16
	v_mul_f32_e32 v17, v31, v31
	v_fmac_f32_e32 v18, v28, v28
	v_add_f32_e32 v19, v19, v20
	v_fmac_f32_e32 v23, v22, v22
	v_add_f32_e32 v16, v16, v21
	v_fmac_f32_e32 v17, v30, v30
	v_add_f32_e32 v18, v19, v18
	v_add_f32_e32 v16, v23, v16
	v_add_f32_e32 v17, v17, v18
	v_and_b32_e32 v18, 64, v186
	v_add_f32_e32 v16, v16, v17
	v_xor_b32_e32 v17, 16, v186
	v_add_u32_e32 v18, 64, v18
	v_cmp_lt_i32_e32 vcc, v17, v18
	s_nop 1
	v_cndmask_b32_e32 v17, v186, v17, vcc
	v_lshlrev_b32_e32 v17, 2, v17
	v_mov_b32_e32 v17, v16
	s_nop 1
	v_permlane16_swap_b32_e32 v16, v17
	s_nop 1
	s_waitcnt lgkmcnt(0)
	v_add_f32_e32 v16, v16, v17
	v_xor_b32_e32 v17, 32, v186
	v_cmp_lt_i32_e32 vcc, v17, v18
	s_nop 1
	v_cndmask_b32_e32 v17, v186, v17, vcc
	v_lshlrev_b32_e32 v17, 2, v17
	v_mov_b32_e32 v17, v16
	s_nop 1
	v_permlane32_swap_b32_e32 v16, v17
	s_nop 1
	s_and_saveexec_b64 s[64:65], s[4:5]
	s_cbranch_execz .LBB0_453
	v_lshl_add_u64 v[18:19], v[144:145], 2, s[28:29]
	s_waitcnt lgkmcnt(0)
	v_add_f32_e32 v16, v16, v17
	global_atomic_add_f32 v[18:19], v16, off offset:640

.LBB0_454:
	v_add_co_u32_e32 v22, vcc, s74, v112
	v_pk_mul_f32 v[2:3], v[2:3], 0.5 op_sel_hi:[1,0]
	s_nop 0
	v_addc_co_u32_e32 v23, vcc, 0, v113, vcc
	v_pk_mul_f32 v[0:1], v[0:1], 0.5 op_sel_hi:[1,0]
	v_pk_mul_f32 v[6:7], v[6:7], 0.5 op_sel_hi:[1,0]
	v_pk_mul_f32 v[4:5], v[4:5], 0.5 op_sel_hi:[1,0]
	v_cvt_pk_bf16_f32 v16, v0, v1
	s_waitcnt lgkmcnt(0)
	v_cvt_pk_bf16_f32 v17, v2, v3
	v_lshl_add_u64 v[20:21], v[112:113], 0, s[52:53]
	v_cvt_pk_bf16_f32 v18, v4, v5
	v_cvt_pk_bf16_f32 v19, v6, v7
	v_pk_mul_f32 v[10:11], v[10:11], 0.5 op_sel_hi:[1,0]
	v_pk_mul_f32 v[8:9], v[8:9], 0.5 op_sel_hi:[1,0]
	v_pk_mul_f32 v[14:15], v[14:15], 0.5 op_sel_hi:[1,0]
	v_pk_mul_f32 v[12:13], v[12:13], 0.5 op_sel_hi:[1,0]
	s_and_b64 vcc, exec, s[8:9]
	global_store_dwordx4 v[22:23], v[16:19], off
	s_nop 1
	v_cvt_pk_bf16_f32 v16, v8, v9
	v_cvt_pk_bf16_f32 v17, v10, v11
	v_cvt_pk_bf16_f32 v18, v12, v13
	v_cvt_pk_bf16_f32 v19, v14, v15
	global_store_dwordx4 v[20:21], v[16:19], off offset:256
	s_cbranch_vccnz .LBB0_458
	v_mul_f32_e32 v5, v5, v5
	v_mul_f32_e32 v1, v1, v1
	v_fmac_f32_e32 v5, v4, v4
	v_fmac_f32_e32 v1, v0, v0
	v_mul_f32_e32 v0, v3, v3
	v_mul_f32_e32 v3, v9, v9
	v_mul_f32_e32 v4, v11, v11
	v_fmac_f32_e32 v0, v2, v2
	v_mul_f32_e32 v2, v13, v13
	v_fmac_f32_e32 v3, v8, v8
	v_fmac_f32_e32 v4, v10, v10
	v_mul_f32_e32 v7, v7, v7
	v_add_f32_e32 v0, v1, v0
	v_mul_f32_e32 v1, v15, v15
	v_fmac_f32_e32 v2, v12, v12
	v_add_f32_e32 v3, v3, v4
	v_fmac_f32_e32 v7, v6, v6
	v_add_f32_e32 v0, v0, v5
	v_fmac_f32_e32 v1, v14, v14
	v_add_f32_e32 v2, v3, v2
	v_add_f32_e32 v0, v7, v0
	v_add_f32_e32 v1, v1, v2
	v_and_b32_e32 v2, 64, v186
	v_add_f32_e32 v0, v0, v1
	v_xor_b32_e32 v1, 16, v186
	v_add_u32_e32 v2, 64, v2
	v_cmp_lt_i32_e32 vcc, v1, v2
	s_nop 1
	v_cndmask_b32_e32 v1, v186, v1, vcc
	v_lshlrev_b32_e32 v1, 2, v1
	v_mov_b32_e32 v1, v0
	s_nop 1
	v_permlane16_swap_b32_e32 v0, v1
	s_nop 1
	s_waitcnt lgkmcnt(0)
	v_add_f32_e32 v0, v0, v1
	v_xor_b32_e32 v1, 32, v186
	v_cmp_lt_i32_e32 vcc, v1, v2
	s_nop 1
	v_cndmask_b32_e32 v1, v186, v1, vcc
	v_lshlrev_b32_e32 v1, 2, v1
	v_mov_b32_e32 v1, v0
	s_nop 1
	v_permlane32_swap_b32_e32 v0, v1
	s_nop 1
	s_and_saveexec_b64 s[8:9], s[4:5]
	s_cbranch_execz .LBB0_457
	v_lshl_add_u64 v[2:3], v[144:145], 2, s[28:29]
	s_waitcnt lgkmcnt(0)
	v_add_f32_e32 v0, v0, v1
	global_atomic_add_f32 v[2:3], v0, off offset:704

.LBB0_1256:
	v_mul_f32_e32 v153, v117, v117
	v_mul_f32_e32 v154, v119, v119
	v_fmac_f32_e32 v153, v116, v116
	v_fmac_f32_e32 v154, v118, v118
	v_add_f32_e32 v153, v153, v154
	v_mul_f32_e32 v154, v125, v125
	v_fmac_f32_e32 v154, v124, v124
	v_add_f32_e32 v153, v153, v154
	v_mul_f32_e32 v154, v127, v127
	v_fmac_f32_e32 v154, v126, v126
	v_add_f32_e32 v153, v154, v153
	v_cvt_pk_bf16_f32 v154, v116, v117
	v_mul_f32_e32 v116, v113, v113
	v_mul_f32_e32 v117, v115, v115
	v_fmac_f32_e32 v116, v112, v112
	v_fmac_f32_e32 v117, v114, v114
	v_add_f32_e32 v116, v116, v117
	v_mul_f32_e32 v117, v121, v121
	v_fmac_f32_e32 v117, v120, v120
	v_add_f32_e32 v116, v116, v117
	v_mul_f32_e32 v117, v123, v123
	v_fmac_f32_e32 v117, v122, v122
	v_cvt_pk_bf16_f32 v155, v118, v119
	v_cvt_pk_bf16_f32 v156, v124, v125
	v_add_f32_e32 v116, v117, v116
	v_and_b32_e32 v124, 64, v152
	v_cvt_pk_bf16_f32 v157, v126, v127
	v_add_f32_e32 v117, v153, v116
	v_xor_b32_e32 v116, 16, v152
	v_add_u32_e32 v126, 64, v124
	v_lshl_add_u32 v146, s54, 8, v148
	v_cmp_lt_i32_e32 vcc, v116, v126
	v_ashrrev_i32_e32 v147, 31, v146
	v_lshl_or_b32 v144, s56, 8, v150
	v_cndmask_b32_e32 v116, v152, v116, vcc
	v_lshlrev_b64 v[118:119], 11, v[146:147]
	v_lshlrev_b32_e32 v116, 2, v116
	v_ashrrev_i32_e32 v145, 31, v144
	v_mov_b32_e32 v127, v117
	s_nop 1
	v_permlane16_swap_b32_e32 v117, v127
	s_nop 1
	v_lshl_add_u64 v[118:119], s[22:23], 0, v[118:119]
	v_lshl_add_u64 v[124:125], v[144:145], 1, v[118:119]
	global_store_dwordx4 v[124:125], v[154:157], off
	v_cvt_pk_bf16_f32 v118, v112, v113
	v_xor_b32_e32 v113, 32, v152
	v_cmp_lt_i32_e32 vcc, v113, v126
	s_waitcnt lgkmcnt(0)
	v_add_f32_e32 v112, v117, v127
	v_cvt_pk_bf16_f32 v119, v114, v115
	v_cvt_pk_bf16_f32 v120, v120, v121
	v_cvt_pk_bf16_f32 v121, v122, v123
	global_store_dwordx4 v[124:125], v[118:121], off offset:256
	v_cndmask_b32_e32 v113, v152, v113, vcc
	v_lshlrev_b32_e32 v117, 2, v113
	v_mov_b32_e32 v113, v112
	s_nop 1
	v_permlane32_swap_b32_e32 v112, v113
	s_nop 1
	s_and_saveexec_b64 s[54:55], s[4:5]
	s_cbranch_execz .LBB0_1258
	v_lshl_add_u64 v[114:115], v[146:147], 2, s[0:1]
	s_waitcnt lgkmcnt(0)
	v_add_f32_e32 v112, v112, v113
	global_atomic_add_f32 v[114:115], v112, off
.LBB0_1258:
	s_or_b64 exec, exec, s[54:55]
	v_mul_f32_e32 v114, v97, v97
	v_mul_f32_e32 v115, v99, v99
	v_fmac_f32_e32 v114, v96, v96
	v_fmac_f32_e32 v115, v98, v98
	v_add_f32_e32 v114, v114, v115
	v_mul_f32_e32 v115, v105, v105
	v_fmac_f32_e32 v115, v104, v104
	v_add_f32_e32 v114, v114, v115
	v_mul_f32_e32 v115, v107, v107
	v_fmac_f32_e32 v115, v106, v106
	v_cvt_pk_bf16_f32 v96, v96, v97
	v_cvt_pk_bf16_f32 v97, v98, v99
	v_cvt_pk_bf16_f32 v98, v104, v105
	v_cvt_pk_bf16_f32 v99, v106, v107
	v_mul_f32_e32 v106, v101, v101
	v_mul_f32_e32 v107, v103, v103
	v_fmac_f32_e32 v106, v100, v100
	v_fmac_f32_e32 v107, v102, v102
	v_add_f32_e32 v106, v106, v107
	v_mul_f32_e32 v107, v109, v109
	v_fmac_f32_e32 v107, v108, v108
	v_add_f32_e32 v106, v106, v107
	v_mul_f32_e32 v107, v111, v111
	v_fmac_f32_e32 v107, v110, v110
	v_add_f32_e32 v114, v115, v114
	v_add_f32_e32 v106, v107, v106
	v_add_f32_e32 v106, v114, v106
	v_or_b32_e32 v112, 16, v146
	v_mov_b32_e32 v107, v106
	s_nop 1
	v_permlane16_swap_b32_e32 v106, v107
	s_nop 1
	s_waitcnt lgkmcnt(0)
	v_ashrrev_i32_e32 v113, 31, v112
	v_lshlrev_b64 v[104:105], 11, v[112:113]
	v_lshl_add_u64 v[104:105], s[22:23], 0, v[104:105]
	v_lshl_add_u64 v[104:105], v[144:145], 1, v[104:105]
	global_store_dwordx4 v[104:105], v[96:99], off
	s_nop 1
	v_add_f32_e32 v96, v106, v107
	v_mov_b32_e32 v97, v96
	s_nop 1
	v_permlane32_swap_b32_e32 v96, v97
	s_nop 1
	v_cvt_pk_bf16_f32 v98, v100, v101
	v_cvt_pk_bf16_f32 v99, v102, v103
	v_cvt_pk_bf16_f32 v100, v108, v109
	v_cvt_pk_bf16_f32 v101, v110, v111
	global_store_dwordx4 v[104:105], v[98:101], off offset:256
	s_and_saveexec_b64 s[54:55], s[4:5]
	s_cbranch_execz .LBB0_1260
	v_lshl_add_u64 v[98:99], v[112:113], 2, s[0:1]
	s_waitcnt lgkmcnt(0)
	v_add_f32_e32 v96, v96, v97
	global_atomic_add_f32 v[98:99], v96, off
.LBB0_1260:
	s_or_b64 exec, exec, s[54:55]
	v_mul_f32_e32 v98, v81, v81
	v_mul_f32_e32 v99, v83, v83
	v_fmac_f32_e32 v98, v80, v80
	v_fmac_f32_e32 v99, v82, v82
	v_add_f32_e32 v98, v98, v99
	v_mul_f32_e32 v99, v89, v89
	v_fmac_f32_e32 v99, v88, v88
	v_add_f32_e32 v98, v98, v99
	v_mul_f32_e32 v99, v91, v91
	v_fmac_f32_e32 v99, v90, v90
	v_cvt_pk_bf16_f32 v80, v80, v81
	v_cvt_pk_bf16_f32 v81, v82, v83
	v_cvt_pk_bf16_f32 v82, v88, v89
	v_cvt_pk_bf16_f32 v83, v90, v91
	v_mul_f32_e32 v90, v85, v85
	v_mul_f32_e32 v91, v87, v87
	v_fmac_f32_e32 v90, v84, v84
	v_fmac_f32_e32 v91, v86, v86
	v_add_f32_e32 v90, v90, v91
	v_mul_f32_e32 v91, v93, v93
	v_fmac_f32_e32 v91, v92, v92
	v_add_f32_e32 v90, v90, v91
	v_mul_f32_e32 v91, v95, v95
	v_fmac_f32_e32 v91, v94, v94
	v_add_f32_e32 v98, v99, v98
	v_add_f32_e32 v90, v91, v90
	v_add_f32_e32 v90, v98, v90
	v_or_b32_e32 v96, 32, v146
	v_mov_b32_e32 v91, v90
	s_nop 1
	v_permlane16_swap_b32_e32 v90, v91
	s_nop 1
	s_waitcnt lgkmcnt(0)
	v_ashrrev_i32_e32 v97, 31, v96
	v_lshlrev_b64 v[88:89], 11, v[96:97]
	v_lshl_add_u64 v[88:89], s[22:23], 0, v[88:89]
	v_lshl_add_u64 v[88:89], v[144:145], 1, v[88:89]
	global_store_dwordx4 v[88:89], v[80:83], off
	s_nop 1
	v_add_f32_e32 v80, v90, v91
	v_mov_b32_e32 v81, v80
	s_nop 1
	v_permlane32_swap_b32_e32 v80, v81
	s_nop 1
	v_cvt_pk_bf16_f32 v82, v84, v85
	v_cvt_pk_bf16_f32 v83, v86, v87
	v_cvt_pk_bf16_f32 v84, v92, v93
	v_cvt_pk_bf16_f32 v85, v94, v95
	global_store_dwordx4 v[88:89], v[82:85], off offset:256
	s_and_saveexec_b64 s[54:55], s[4:5]
	s_cbranch_execz .LBB0_1262
	v_lshl_add_u64 v[82:83], v[96:97], 2, s[0:1]
	s_waitcnt lgkmcnt(0)
	v_add_f32_e32 v80, v80, v81
	global_atomic_add_f32 v[82:83], v80, off
.LBB0_1262:
	s_or_b64 exec, exec, s[54:55]
	v_mul_f32_e32 v82, v57, v57
	v_mul_f32_e32 v83, v59, v59
	v_fmac_f32_e32 v82, v56, v56
	v_fmac_f32_e32 v83, v58, v58
	v_add_f32_e32 v82, v82, v83
	v_mul_f32_e32 v83, v69, v69
	v_fmac_f32_e32 v83, v68, v68
	v_add_f32_e32 v82, v82, v83
	v_mul_f32_e32 v83, v71, v71
	v_fmac_f32_e32 v83, v70, v70
	v_cvt_pk_bf16_f32 v56, v56, v57
	v_cvt_pk_bf16_f32 v57, v58, v59
	v_cvt_pk_bf16_f32 v58, v68, v69
	v_cvt_pk_bf16_f32 v59, v70, v71
	v_mul_f32_e32 v70, v65, v65
	v_mul_f32_e32 v71, v67, v67
	v_fmac_f32_e32 v70, v64, v64
	v_fmac_f32_e32 v71, v66, v66
	v_add_f32_e32 v70, v70, v71
	v_mul_f32_e32 v71, v73, v73
	v_fmac_f32_e32 v71, v72, v72
	v_add_f32_e32 v70, v70, v71
	v_mul_f32_e32 v71, v75, v75
	v_fmac_f32_e32 v71, v74, v74
	v_add_f32_e32 v82, v83, v82
	v_add_f32_e32 v70, v71, v70
	v_add_f32_e32 v70, v82, v70
	v_or_b32_e32 v80, 48, v146
	v_mov_b32_e32 v71, v70
	s_nop 1
	v_permlane16_swap_b32_e32 v70, v71
	s_nop 1
	s_waitcnt lgkmcnt(0)
	v_ashrrev_i32_e32 v81, 31, v80
	v_lshlrev_b64 v[68:69], 11, v[80:81]
	v_lshl_add_u64 v[68:69], s[22:23], 0, v[68:69]
	v_lshl_add_u64 v[68:69], v[144:145], 1, v[68:69]
	global_store_dwordx4 v[68:69], v[56:59], off
	v_cvt_pk_bf16_f32 v64, v64, v65
	v_cvt_pk_bf16_f32 v65, v66, v67
	v_cvt_pk_bf16_f32 v66, v72, v73
	v_cvt_pk_bf16_f32 v67, v74, v75
	global_store_dwordx4 v[68:69], v[64:67], off offset:256
	s_nop 0
	v_add_f32_e32 v56, v70, v71
	v_mov_b32_e32 v57, v56
	s_nop 1
	v_permlane32_swap_b32_e32 v56, v57
	s_nop 1
	s_and_saveexec_b64 s[54:55], s[4:5]
	s_cbranch_execz .LBB0_1264
	v_lshl_add_u64 v[58:59], v[80:81], 2, s[0:1]
	s_waitcnt lgkmcnt(0)
	v_add_f32_e32 v56, v56, v57
	global_atomic_add_f32 v[58:59], v56, off
.LBB0_1264:
	s_or_b64 exec, exec, s[54:55]
	v_mul_f32_e32 v58, v45, v45
	v_mul_f32_e32 v59, v47, v47
	v_fmac_f32_e32 v58, v44, v44
	v_fmac_f32_e32 v59, v46, v46
	v_add_f32_e32 v58, v58, v59
	v_mul_f32_e32 v59, v53, v53
	v_fmac_f32_e32 v59, v52, v52
	v_add_f32_e32 v58, v58, v59
	v_mul_f32_e32 v59, v55, v55
	v_fmac_f32_e32 v59, v54, v54
	v_cvt_pk_bf16_f32 v44, v44, v45
	v_cvt_pk_bf16_f32 v45, v46, v47
	v_cvt_pk_bf16_f32 v46, v52, v53
	v_cvt_pk_bf16_f32 v47, v54, v55
	v_mul_f32_e32 v54, v49, v49
	v_mul_f32_e32 v55, v51, v51
	v_fmac_f32_e32 v54, v48, v48
	v_fmac_f32_e32 v55, v50, v50
	v_add_f32_e32 v54, v54, v55
	v_mul_f32_e32 v55, v61, v61
	v_fmac_f32_e32 v55, v60, v60
	v_add_f32_e32 v54, v54, v55
	v_mul_f32_e32 v55, v63, v63
	v_fmac_f32_e32 v55, v62, v62
	v_add_f32_e32 v58, v59, v58
	v_add_f32_e32 v54, v55, v54
	v_add_f32_e32 v54, v58, v54
	v_add_u32_e32 v56, 0x80, v146
	v_mov_b32_e32 v55, v54
	s_nop 1
	v_permlane16_swap_b32_e32 v54, v55
	s_nop 1
	s_waitcnt lgkmcnt(0)
	v_ashrrev_i32_e32 v57, 31, v56
	v_lshlrev_b64 v[52:53], 11, v[56:57]
	v_lshl_add_u64 v[52:53], s[22:23], 0, v[52:53]
	v_lshl_add_u64 v[52:53], v[144:145], 1, v[52:53]
	global_store_dwordx4 v[52:53], v[44:47], off
	s_nop 1
	v_add_f32_e32 v44, v54, v55
	v_mov_b32_e32 v45, v44
	s_nop 1
	v_permlane32_swap_b32_e32 v44, v45
	s_nop 1
	v_cvt_pk_bf16_f32 v46, v48, v49
	v_cvt_pk_bf16_f32 v47, v50, v51
	v_cvt_pk_bf16_f32 v48, v60, v61
	v_cvt_pk_bf16_f32 v49, v62, v63
	global_store_dwordx4 v[52:53], v[46:49], off offset:256
	s_and_saveexec_b64 s[54:55], s[4:5]
	s_cbranch_execz .LBB0_1266
	v_lshl_add_u64 v[46:47], v[56:57], 2, s[0:1]
	s_waitcnt lgkmcnt(0)
	v_add_f32_e32 v44, v44, v45
	global_atomic_add_f32 v[46:47], v44, off
.LBB0_1266:
	s_or_b64 exec, exec, s[54:55]
	v_mul_f32_e32 v46, v17, v17
	v_mul_f32_e32 v47, v19, v19
	v_fmac_f32_e32 v46, v16, v16
	v_fmac_f32_e32 v47, v18, v18
	v_add_f32_e32 v46, v46, v47
	v_mul_f32_e32 v47, v25, v25
	v_fmac_f32_e32 v47, v24, v24
	v_add_f32_e32 v46, v46, v47
	v_mul_f32_e32 v47, v27, v27
	v_fmac_f32_e32 v47, v26, v26
	v_cvt_pk_bf16_f32 v16, v16, v17
	v_cvt_pk_bf16_f32 v17, v18, v19
	v_cvt_pk_bf16_f32 v18, v24, v25
	v_cvt_pk_bf16_f32 v19, v26, v27
	v_mul_f32_e32 v26, v21, v21
	v_mul_f32_e32 v27, v23, v23
	v_fmac_f32_e32 v26, v20, v20
	v_fmac_f32_e32 v27, v22, v22
	v_add_f32_e32 v26, v26, v27
	v_mul_f32_e32 v27, v77, v77
	v_fmac_f32_e32 v27, v76, v76
	v_add_f32_e32 v26, v26, v27
	v_mul_f32_e32 v27, v79, v79
	v_fmac_f32_e32 v27, v78, v78
	v_add_f32_e32 v46, v47, v46
	v_add_f32_e32 v26, v27, v26
	v_add_f32_e32 v26, v46, v26
	v_add_u32_e32 v44, 0x90, v146
	v_mov_b32_e32 v27, v26
	s_nop 1
	v_permlane16_swap_b32_e32 v26, v27
	s_nop 1
	s_waitcnt lgkmcnt(0)
	v_ashrrev_i32_e32 v45, 31, v44
	v_lshlrev_b64 v[24:25], 11, v[44:45]
	v_lshl_add_u64 v[24:25], s[22:23], 0, v[24:25]
	v_lshl_add_u64 v[24:25], v[144:145], 1, v[24:25]
	global_store_dwordx4 v[24:25], v[16:19], off
	s_nop 1
	v_add_f32_e32 v16, v26, v27
	v_mov_b32_e32 v17, v16
	s_nop 1
	v_permlane32_swap_b32_e32 v16, v17
	s_nop 1
	v_cvt_pk_bf16_f32 v18, v20, v21
	v_cvt_pk_bf16_f32 v19, v22, v23
	v_cvt_pk_bf16_f32 v20, v76, v77
	v_cvt_pk_bf16_f32 v21, v78, v79
	global_store_dwordx4 v[24:25], v[18:21], off offset:256
	s_and_saveexec_b64 s[54:55], s[4:5]
	s_cbranch_execz .LBB0_1268
	v_lshl_add_u64 v[18:19], v[44:45], 2, s[0:1]
	s_waitcnt lgkmcnt(0)
	v_add_f32_e32 v16, v16, v17
	global_atomic_add_f32 v[18:19], v16, off
.LBB0_1268:
	s_or_b64 exec, exec, s[54:55]
	v_mul_f32_e32 v18, v29, v29
	v_mul_f32_e32 v19, v31, v31
	v_mul_f32_e32 v25, v33, v33
	v_mul_f32_e32 v26, v35, v35
	v_fmac_f32_e32 v18, v28, v28
	v_fmac_f32_e32 v19, v30, v30
	v_fmac_f32_e32 v25, v32, v32
	v_fmac_f32_e32 v26, v34, v34
	v_add_f32_e32 v18, v18, v19
	v_mul_f32_e32 v19, v37, v37
	v_add_f32_e32 v25, v25, v26
	v_mul_f32_e32 v26, v41, v41
	v_fmac_f32_e32 v19, v36, v36
	v_fmac_f32_e32 v26, v40, v40
	v_add_f32_e32 v18, v18, v19
	v_mul_f32_e32 v19, v39, v39
	v_add_f32_e32 v25, v25, v26
	v_mul_f32_e32 v26, v43, v43
	v_fmac_f32_e32 v19, v38, v38
	v_fmac_f32_e32 v26, v42, v42
	v_add_f32_e32 v24, v19, v18
	v_add_f32_e32 v25, v26, v25
	v_add_f32_e32 v26, v24, v25
	v_add_u32_e32 v16, 0xa0, v146
	v_mov_b32_e32 v27, v26
	s_nop 1
	v_permlane16_swap_b32_e32 v26, v27
	s_nop 1
	s_waitcnt lgkmcnt(0)
	v_ashrrev_i32_e32 v17, 31, v16
	v_lshlrev_b64 v[22:23], 11, v[16:17]
	v_lshl_add_u64 v[22:23], s[22:23], 0, v[22:23]
	v_cvt_pk_bf16_f32 v18, v28, v29
	v_lshl_add_u64 v[24:25], v[144:145], 1, v[22:23]
	v_cvt_pk_bf16_f32 v19, v30, v31
	v_cvt_pk_bf16_f32 v20, v36, v37
	v_cvt_pk_bf16_f32 v21, v38, v39
	global_store_dwordx4 v[24:25], v[18:21], off
	s_nop 1
	v_add_f32_e32 v18, v26, v27
	v_mov_b32_e32 v19, v18
	s_nop 1
	v_permlane32_swap_b32_e32 v18, v19
	s_nop 1
	v_cvt_pk_bf16_f32 v20, v32, v33
	v_cvt_pk_bf16_f32 v21, v34, v35
	v_cvt_pk_bf16_f32 v22, v40, v41
	v_cvt_pk_bf16_f32 v23, v42, v43
	global_store_dwordx4 v[24:25], v[20:23], off offset:256
	s_and_saveexec_b64 s[54:55], s[4:5]
	s_cbranch_execz .LBB0_1270
	v_lshl_add_u64 v[16:17], v[16:17], 2, s[0:1]
	s_waitcnt lgkmcnt(0)
	v_add_f32_e32 v18, v18, v19
	global_atomic_add_f32 v[16:17], v18, off
.LBB0_1270:
	s_or_b64 exec, exec, s[54:55]
	v_mul_f32_e32 v18, v1, v1
	s_waitcnt lgkmcnt(0)
	v_mul_f32_e32 v19, v3, v3
	v_fmac_f32_e32 v18, v0, v0
	v_fmac_f32_e32 v19, v2, v2
	v_add_f32_e32 v18, v18, v19
	v_mul_f32_e32 v19, v9, v9
	v_fmac_f32_e32 v19, v8, v8
	v_add_f32_e32 v18, v18, v19
	v_mul_f32_e32 v19, v11, v11
	v_fmac_f32_e32 v19, v10, v10
	v_cvt_pk_bf16_f32 v0, v0, v1
	v_cvt_pk_bf16_f32 v1, v2, v3
	v_cvt_pk_bf16_f32 v2, v8, v9
	v_cvt_pk_bf16_f32 v3, v10, v11
	v_mul_f32_e32 v10, v5, v5
	v_mul_f32_e32 v11, v7, v7
	v_fmac_f32_e32 v10, v4, v4
	v_fmac_f32_e32 v11, v6, v6
	v_add_f32_e32 v10, v10, v11
	v_mul_f32_e32 v11, v13, v13
	v_fmac_f32_e32 v11, v12, v12
	v_add_f32_e32 v10, v10, v11
	v_mul_f32_e32 v11, v15, v15
	v_fmac_f32_e32 v11, v14, v14
	v_add_f32_e32 v18, v19, v18
	v_add_f32_e32 v10, v11, v10
	v_add_f32_e32 v10, v18, v10
	v_add_u32_e32 v16, 0xb0, v146
	v_mov_b32_e32 v11, v10
	s_nop 1
	v_permlane16_swap_b32_e32 v10, v11
	s_nop 1
	v_ashrrev_i32_e32 v17, 31, v16
	v_lshlrev_b64 v[8:9], 11, v[16:17]
	v_lshl_add_u64 v[8:9], s[22:23], 0, v[8:9]
	v_lshl_add_u64 v[8:9], v[144:145], 1, v[8:9]
	global_store_dwordx4 v[8:9], v[0:3], off
	s_waitcnt lgkmcnt(0)
	s_nop 0
	v_add_f32_e32 v0, v10, v11
	v_mov_b32_e32 v1, v0
	s_nop 1
	v_permlane32_swap_b32_e32 v0, v1
	s_nop 1
	v_cvt_pk_bf16_f32 v2, v4, v5
	v_cvt_pk_bf16_f32 v3, v6, v7
	v_cvt_pk_bf16_f32 v4, v12, v13
	v_cvt_pk_bf16_f32 v5, v14, v15
	global_store_dwordx4 v[8:9], v[2:5], off offset:256
	s_and_saveexec_b64 s[54:55], s[4:5]
	s_cbranch_execz .LBB0_1272
	v_lshl_add_u64 v[2:3], v[16:17], 2, s[0:1]
	s_waitcnt lgkmcnt(0)
	v_add_f32_e32 v0, v0, v1
	global_atomic_add_f32 v[2:3], v0, off

.LBB0_1419:
	v_and_b32_e32 v129, 64, v182
	v_xor_b32_e32 v128, 16, v182
	v_add_u32_e32 v129, 64, v129
	v_cmp_lt_i32_e32 vcc, v128, v129
	v_mul_f32_e32 v131, v31, v31
	v_fmac_f32_e32 v131, v30, v30
	v_cndmask_b32_e32 v128, v182, v128, vcc
	v_lshlrev_b32_e32 v130, 2, v128
	v_mul_f32_e32 v128, v29, v29
	v_fmac_f32_e32 v128, v28, v28
	v_add_f32_e32 v128, v128, v131
	v_mul_f32_e32 v131, v37, v37
	v_fmac_f32_e32 v131, v36, v36
	v_add_f32_e32 v128, v128, v131
	v_mul_f32_e32 v131, v39, v39
	v_fmac_f32_e32 v131, v38, v38
	v_add_f32_e32 v128, v131, v128
	v_mul_f32_e32 v131, v105, v105
	v_mul_f32_e32 v132, v107, v107
	v_fmac_f32_e32 v131, v104, v104
	v_fmac_f32_e32 v132, v106, v106
	v_add_f32_e32 v131, v131, v132
	v_mul_f32_e32 v132, v109, v109
	v_fmac_f32_e32 v132, v108, v108
	v_add_f32_e32 v131, v131, v132
	v_mul_f32_e32 v132, v111, v111
	v_fmac_f32_e32 v132, v110, v110
	v_add_f32_e32 v131, v132, v131
	v_add_f32_e32 v128, v128, v131
	v_mul_f32_e32 v131, 0x3e800000, v128
	ds_bpermute_b32 v132, v130, v131
	v_xor_b32_e32 v131, 32, v182
	v_cmp_lt_i32_e32 vcc, v131, v129
	v_lshl_add_u32 v160, s78, 8, v178
	v_ashrrev_i32_e32 v161, 31, v160
	v_cndmask_b32_e32 v129, v182, v131, vcc
	v_lshlrev_b32_e32 v131, 2, v129
	s_waitcnt lgkmcnt(0)
	v_fmac_f32_e32 v132, 0x3e800000, v128
	v_mov_b32_e32 v133, v132
	s_nop 1
	v_permlane32_swap_b32_e32 v132, v133
	s_nop 1
	v_lshl_add_u64 v[128:129], v[160:161], 2, s[34:35]
	s_and_saveexec_b64 s[48:49], s[0:1]
	s_cbranch_execz .LBB0_1421
	s_waitcnt lgkmcnt(0)
	v_add_f32_e32 v132, v132, v133
	global_atomic_add_f32 v[128:129], v132, off
.LBB0_1421:
	s_or_b64 exec, exec, s[48:49]
	v_mul_f32_e32 v132, v45, v45
	s_waitcnt lgkmcnt(0)
	v_mul_f32_e32 v133, v47, v47
	v_fmac_f32_e32 v132, v44, v44
	v_fmac_f32_e32 v133, v46, v46
	v_add_f32_e32 v132, v132, v133
	v_mul_f32_e32 v133, v53, v53
	v_fmac_f32_e32 v133, v52, v52
	v_add_f32_e32 v132, v132, v133
	v_mul_f32_e32 v133, v55, v55
	v_fmac_f32_e32 v133, v54, v54
	v_add_f32_e32 v132, v133, v132
	v_mul_f32_e32 v133, v113, v113
	v_mul_f32_e32 v134, v115, v115
	v_fmac_f32_e32 v133, v112, v112
	v_fmac_f32_e32 v134, v114, v114
	v_add_f32_e32 v133, v133, v134
	v_mul_f32_e32 v134, v125, v125
	v_fmac_f32_e32 v134, v124, v124
	v_add_f32_e32 v133, v133, v134
	v_mul_f32_e32 v134, v127, v127
	v_fmac_f32_e32 v134, v126, v126
	v_add_f32_e32 v133, v134, v133
	v_add_f32_e32 v133, v132, v133
	v_mul_f32_e32 v132, 0x3e800000, v133
	ds_bpermute_b32 v132, v130, v132
	s_waitcnt lgkmcnt(0)
	v_fmac_f32_e32 v132, 0x3e800000, v133
	v_mov_b32_e32 v133, v132
	s_nop 1
	v_permlane32_swap_b32_e32 v132, v133
	s_nop 1
	s_and_saveexec_b64 s[48:49], s[0:1]
	s_cbranch_execz .LBB0_1423
	s_waitcnt lgkmcnt(0)
	v_add_f32_e32 v132, v132, v133
	global_atomic_add_f32 v[128:129], v132, off offset:64
.LBB0_1423:
	s_or_b64 exec, exec, s[48:49]
	v_mul_f32_e32 v132, v33, v33
	s_waitcnt lgkmcnt(0)
	v_mul_f32_e32 v133, v35, v35
	v_fmac_f32_e32 v132, v32, v32
	v_fmac_f32_e32 v133, v34, v34
	v_add_f32_e32 v132, v132, v133
	v_mul_f32_e32 v133, v25, v25
	v_fmac_f32_e32 v133, v24, v24
	v_add_f32_e32 v132, v132, v133
	v_mul_f32_e32 v133, v27, v27
	v_fmac_f32_e32 v133, v26, v26
	v_add_f32_e32 v132, v133, v132
	v_mul_f32_e32 v133, v89, v89
	v_mul_f32_e32 v134, v91, v91
	v_fmac_f32_e32 v133, v88, v88
	v_fmac_f32_e32 v134, v90, v90
	v_add_f32_e32 v133, v133, v134
	v_mul_f32_e32 v134, v93, v93
	v_fmac_f32_e32 v134, v92, v92
	v_add_f32_e32 v133, v133, v134
	v_mul_f32_e32 v134, v95, v95
	v_fmac_f32_e32 v134, v94, v94
	v_add_f32_e32 v133, v134, v133
	v_add_f32_e32 v133, v132, v133
	v_mul_f32_e32 v132, 0x3e800000, v133
	ds_bpermute_b32 v132, v130, v132
	s_waitcnt lgkmcnt(0)
	v_fmac_f32_e32 v132, 0x3e800000, v133
	v_mov_b32_e32 v133, v132
	s_nop 1
	v_permlane32_swap_b32_e32 v132, v133
	s_nop 1
	s_and_saveexec_b64 s[48:49], s[0:1]
	s_cbranch_execz .LBB0_1425
	s_waitcnt lgkmcnt(0)
	v_add_f32_e32 v132, v132, v133
	global_atomic_add_f32 v[128:129], v132, off offset:128
.LBB0_1425:
	s_or_b64 exec, exec, s[48:49]
	v_mul_f32_e32 v132, v13, v13
	s_waitcnt lgkmcnt(0)
	v_mul_f32_e32 v133, v15, v15
	v_fmac_f32_e32 v132, v12, v12
	v_fmac_f32_e32 v133, v14, v14
	v_add_f32_e32 v132, v132, v133
	v_mul_f32_e32 v133, v9, v9
	v_fmac_f32_e32 v133, v8, v8
	v_add_f32_e32 v132, v132, v133
	v_mul_f32_e32 v133, v11, v11
	v_fmac_f32_e32 v133, v10, v10
	v_add_f32_e32 v132, v133, v132
	v_mul_f32_e32 v133, v69, v69
	v_mul_f32_e32 v134, v71, v71
	v_fmac_f32_e32 v133, v68, v68
	v_fmac_f32_e32 v134, v70, v70
	v_add_f32_e32 v133, v133, v134
	v_mul_f32_e32 v134, v77, v77
	v_fmac_f32_e32 v134, v76, v76
	v_add_f32_e32 v133, v133, v134
	v_mul_f32_e32 v134, v79, v79
	v_fmac_f32_e32 v134, v78, v78
	v_add_f32_e32 v133, v134, v133
	v_add_f32_e32 v133, v132, v133
	v_mul_f32_e32 v132, 0x3e800000, v133
	ds_bpermute_b32 v132, v130, v132
	s_waitcnt lgkmcnt(0)
	v_fmac_f32_e32 v132, 0x3e800000, v133
	v_mov_b32_e32 v133, v132
	s_nop 1
	v_permlane32_swap_b32_e32 v132, v133
	s_nop 1
	s_and_saveexec_b64 s[48:49], s[0:1]
	s_cbranch_execz .LBB0_1427
	s_waitcnt lgkmcnt(0)
	v_add_f32_e32 v132, v132, v133
	global_atomic_add_f32 v[128:129], v132, off offset:192
.LBB0_1427:
	s_or_b64 exec, exec, s[48:49]
	v_mul_f32_e32 v132, v73, v73
	s_waitcnt lgkmcnt(0)
	v_mul_f32_e32 v133, v75, v75
	v_fmac_f32_e32 v132, v72, v72
	v_fmac_f32_e32 v133, v74, v74
	v_add_f32_e32 v132, v132, v133
	v_mul_f32_e32 v133, v65, v65
	v_fmac_f32_e32 v133, v64, v64
	v_add_f32_e32 v132, v132, v133
	v_mul_f32_e32 v133, v67, v67
	v_fmac_f32_e32 v133, v66, v66
	v_add_f32_e32 v132, v133, v132
	v_mul_f32_e32 v133, v117, v117
	v_mul_f32_e32 v134, v119, v119
	v_fmac_f32_e32 v133, v116, v116
	v_fmac_f32_e32 v134, v118, v118
	v_add_f32_e32 v133, v133, v134
	v_mul_f32_e32 v134, v121, v121
	v_fmac_f32_e32 v134, v120, v120
	v_add_f32_e32 v133, v133, v134
	v_mul_f32_e32 v134, v123, v123
	v_fmac_f32_e32 v134, v122, v122
	v_add_f32_e32 v133, v134, v133
	v_add_f32_e32 v133, v132, v133
	v_mul_f32_e32 v132, 0x3e800000, v133
	ds_bpermute_b32 v132, v130, v132
	s_waitcnt lgkmcnt(0)
	v_fmac_f32_e32 v132, 0x3e800000, v133
	v_mov_b32_e32 v133, v132
	s_nop 1
	v_permlane32_swap_b32_e32 v132, v133
	s_nop 1
	s_and_saveexec_b64 s[48:49], s[0:1]
	s_cbranch_execz .LBB0_1429
	s_waitcnt lgkmcnt(0)
	v_add_f32_e32 v132, v132, v133
	global_atomic_add_f32 v[128:129], v132, off offset:512
.LBB0_1429:
	s_or_b64 exec, exec, s[48:49]
	v_mul_f32_e32 v132, v49, v49
	s_waitcnt lgkmcnt(0)
	v_mul_f32_e32 v133, v51, v51
	v_fmac_f32_e32 v132, v48, v48
	v_fmac_f32_e32 v133, v50, v50
	v_add_f32_e32 v132, v132, v133
	v_mul_f32_e32 v133, v41, v41
	v_fmac_f32_e32 v133, v40, v40
	v_add_f32_e32 v132, v132, v133
	v_mul_f32_e32 v133, v43, v43
	v_fmac_f32_e32 v133, v42, v42
	v_add_f32_e32 v132, v133, v132
	v_mul_f32_e32 v133, v97, v97
	v_mul_f32_e32 v134, v99, v99
	v_fmac_f32_e32 v133, v96, v96
	v_fmac_f32_e32 v134, v98, v98
	v_add_f32_e32 v133, v133, v134
	v_mul_f32_e32 v134, v101, v101
	v_fmac_f32_e32 v134, v100, v100
	v_add_f32_e32 v133, v133, v134
	v_mul_f32_e32 v134, v103, v103
	v_fmac_f32_e32 v134, v102, v102
	v_add_f32_e32 v133, v134, v133
	v_add_f32_e32 v133, v132, v133
	v_mul_f32_e32 v132, 0x3e800000, v133
	ds_bpermute_b32 v132, v130, v132
	s_waitcnt lgkmcnt(0)
	v_fmac_f32_e32 v132, 0x3e800000, v133
	v_mov_b32_e32 v133, v132
	s_nop 1
	v_permlane32_swap_b32_e32 v132, v133
	s_nop 1
	s_and_saveexec_b64 s[48:49], s[0:1]
	s_cbranch_execz .LBB0_1431
	s_waitcnt lgkmcnt(0)
	v_add_f32_e32 v132, v132, v133
	global_atomic_add_f32 v[128:129], v132, off offset:576
.LBB0_1431:
	s_or_b64 exec, exec, s[48:49]
	v_mul_f32_e32 v132, v21, v21
	s_waitcnt lgkmcnt(0)
	v_mul_f32_e32 v133, v23, v23
	v_fmac_f32_e32 v132, v20, v20
	v_fmac_f32_e32 v133, v22, v22
	v_add_f32_e32 v132, v132, v133
	v_mul_f32_e32 v133, v17, v17
	v_fmac_f32_e32 v133, v16, v16
	v_add_f32_e32 v132, v132, v133
	v_mul_f32_e32 v133, v19, v19
	v_fmac_f32_e32 v133, v18, v18
	v_add_f32_e32 v132, v133, v132
	v_mul_f32_e32 v133, v81, v81
	v_mul_f32_e32 v134, v83, v83
	v_fmac_f32_e32 v133, v80, v80
	v_fmac_f32_e32 v134, v82, v82
	v_add_f32_e32 v133, v133, v134
	v_mul_f32_e32 v134, v85, v85
	v_fmac_f32_e32 v134, v84, v84
	v_add_f32_e32 v133, v133, v134
	v_mul_f32_e32 v134, v87, v87
	v_fmac_f32_e32 v134, v86, v86
	v_add_f32_e32 v133, v134, v133
	v_add_f32_e32 v133, v132, v133
	v_mul_f32_e32 v132, 0x3e800000, v133
	ds_bpermute_b32 v132, v130, v132
	s_waitcnt lgkmcnt(0)
	v_fmac_f32_e32 v132, 0x3e800000, v133
	v_mov_b32_e32 v133, v132
	s_nop 1
	v_permlane32_swap_b32_e32 v132, v133
	s_nop 1
	s_and_saveexec_b64 s[48:49], s[0:1]
	s_cbranch_execz .LBB0_1433
	s_waitcnt lgkmcnt(0)
	v_add_f32_e32 v132, v132, v133
	global_atomic_add_f32 v[128:129], v132, off offset:640
.LBB0_1433:
	s_or_b64 exec, exec, s[48:49]
	v_mul_f32_e32 v132, v5, v5
	s_waitcnt lgkmcnt(0)
	v_mul_f32_e32 v133, v7, v7
	v_fmac_f32_e32 v132, v4, v4
	v_fmac_f32_e32 v133, v6, v6
	v_add_f32_e32 v132, v132, v133
	v_mul_f32_e32 v133, v1, v1
	v_fmac_f32_e32 v133, v0, v0
	v_add_f32_e32 v132, v132, v133
	v_mul_f32_e32 v133, v3, v3
	v_fmac_f32_e32 v133, v2, v2
	v_add_f32_e32 v132, v133, v132
	v_mul_f32_e32 v133, v57, v57
	v_mul_f32_e32 v134, v59, v59
	v_fmac_f32_e32 v133, v56, v56
	v_fmac_f32_e32 v134, v58, v58
	v_add_f32_e32 v133, v133, v134
	v_mul_f32_e32 v134, v61, v61
	v_fmac_f32_e32 v134, v60, v60
	v_add_f32_e32 v133, v133, v134
	v_mul_f32_e32 v134, v63, v63
	v_fmac_f32_e32 v134, v62, v62
	v_add_f32_e32 v133, v134, v133
	v_add_f32_e32 v132, v132, v133
	v_mul_f32_e32 v133, 0x3e800000, v132
	ds_bpermute_b32 v130, v130, v133
	s_waitcnt lgkmcnt(0)
	v_fmac_f32_e32 v130, 0x3e800000, v132
	v_mov_b32_e32 v131, v130
	s_nop 1
	v_permlane32_swap_b32_e32 v130, v131
	s_nop 1
	s_and_saveexec_b64 s[48:49], s[0:1]
	s_cbranch_execz .LBB0_1435
	s_waitcnt lgkmcnt(0)
	v_add_f32_e32 v130, v130, v131
	global_atomic_add_f32 v[128:129], v130, off offset:704
